# attention K/V LDS staging: skip the 16 select ops per tile when the filler-row mask is all ones
# baseline (speedup 1.0000x reference)
.LBB0_378:
	s_andn2_b64 vcc, exec, s[22:23]
	s_cbranch_vccnz .LBB0_380
	s_cmp_lg_u32 s82, 0
	s_cselect_b64 s[22:23], -1, 0
	s_xor_b32 s79, s79, 1
	s_or_b64 vcc, s[0:1], s[22:23]
	s_mul_i32 s43, s79, 0x4400
	s_mul_i32 s44, s42, 0x5000
	s_cmp_lg_u32 s82, 0
	s_cbranch_scc0 .Lat1_masked
	v_add3_u32 v95, v179, s43, v180
	v_add3_u32 v107, v179, s44, v181
	s_waitcnt vmcnt(3)
	ds_write_b128 v95, v[2:5]
	s_waitcnt vmcnt(2)
	ds_write_b128 v107, v[10:13] offset:34816
	s_waitcnt vmcnt(1)
	ds_write_b128 v95, v[6:9] offset:8704
	s_waitcnt vmcnt(0)
	ds_write_b128 v107, v[144:147] offset:45056
	s_branch .LBB0_381
.Lat1_masked:
	s_waitcnt vmcnt(3)
	v_cndmask_b32_e32 v5, 0, v5, vcc
	v_cndmask_b32_e32 v4, 0, v4, vcc
	v_cndmask_b32_e32 v3, 0, v3, vcc
	v_cndmask_b32_e32 v2, 0, v2, vcc
	s_waitcnt vmcnt(2)
	v_cndmask_b32_e32 v13, 0, v13, vcc
	v_cndmask_b32_e32 v12, 0, v12, vcc
	v_cndmask_b32_e32 v11, 0, v11, vcc
	v_cndmask_b32_e32 v10, 0, v10, vcc
	s_or_b64 vcc, s[38:39], s[22:23]
	v_add3_u32 v95, v179, s43, v180
	v_add3_u32 v107, v179, s44, v181
	s_waitcnt vmcnt(1)
	v_cndmask_b32_e32 v9, 0, v9, vcc
	v_cndmask_b32_e32 v8, 0, v8, vcc
	v_cndmask_b32_e32 v7, 0, v7, vcc
	v_cndmask_b32_e32 v6, 0, v6, vcc
	s_waitcnt vmcnt(0)
	v_cndmask_b32_e32 v147, 0, v147, vcc
	v_cndmask_b32_e32 v146, 0, v146, vcc
	v_cndmask_b32_e32 v145, 0, v145, vcc
	v_cndmask_b32_e32 v144, 0, v144, vcc
	ds_write_b128 v95, v[2:5]
	ds_write_b128 v107, v[10:13] offset:34816
	ds_write_b128 v95, v[6:9] offset:8704
	ds_write_b128 v107, v[144:147] offset:45056
	s_branch .LBB0_381

.LBB0_394:
	s_andn2_b64 vcc, exec, s[12:13]
	s_cbranch_vccnz .LBB0_396
	s_cmp_lg_u32 s68, 0
	s_cselect_b64 s[12:13], -1, 0
	s_xor_b32 s40, s40, 1
	s_or_b64 vcc, s[0:1], s[12:13]
	s_mul_i32 s43, s40, 0x4400
	s_mul_i32 s44, s42, 0x5000
	s_cmp_lg_u32 s68, 0
	s_cbranch_scc0 .Lat0_masked
	v_add3_u32 v99, v179, s43, v180
	v_add3_u32 v100, v179, s44, v181
	s_waitcnt vmcnt(3)
	ds_write_b128 v99, v[128:131]
	s_waitcnt vmcnt(2)
	ds_write_b128 v100, v[132:135] offset:34816
	s_waitcnt vmcnt(1)
	ds_write_b128 v99, v[136:139] offset:8704
	s_waitcnt vmcnt(0)
	ds_write_b128 v100, v[140:143] offset:45056
	s_branch .LBB0_397
.Lat0_masked:
	s_waitcnt vmcnt(3)
	v_cndmask_b32_e32 v131, 0, v131, vcc
	v_cndmask_b32_e32 v130, 0, v130, vcc
	v_cndmask_b32_e32 v129, 0, v129, vcc
	v_cndmask_b32_e32 v128, 0, v128, vcc
	s_waitcnt vmcnt(2)
	v_cndmask_b32_e32 v135, 0, v135, vcc
	v_cndmask_b32_e32 v134, 0, v134, vcc
	v_cndmask_b32_e32 v133, 0, v133, vcc
	v_cndmask_b32_e32 v132, 0, v132, vcc
	s_or_b64 vcc, s[38:39], s[12:13]
	v_add3_u32 v99, v179, s43, v180
	v_add3_u32 v100, v179, s44, v181
	s_waitcnt vmcnt(1)
	v_cndmask_b32_e32 v139, 0, v139, vcc
	v_cndmask_b32_e32 v138, 0, v138, vcc
	v_cndmask_b32_e32 v137, 0, v137, vcc
	v_cndmask_b32_e32 v136, 0, v136, vcc
	s_waitcnt vmcnt(0)
	v_cndmask_b32_e32 v143, 0, v143, vcc
	v_cndmask_b32_e32 v142, 0, v142, vcc
	v_cndmask_b32_e32 v141, 0, v141, vcc
	v_cndmask_b32_e32 v140, 0, v140, vcc
	ds_write_b128 v99, v[128:131]
	ds_write_b128 v100, v[132:135] offset:34816
	ds_write_b128 v99, v[136:139] offset:8704
	ds_write_b128 v100, v[140:143] offset:45056
	s_branch .LBB0_397
